# next-block prefetch, L2-only (asm guide 7.10): SwiGLU epilogues touch the next unit's first two k-tiles (same weight panel, A panel pm+8) with 2 plain loads/thread; + 64B loop alignment; on top of v69
# speedup vs baseline: 1.0025x; 1.0006x over previous
.LBB0_479:
	v_lshl_add_u32 v142, s36, 8, v148
	v_ashrrev_i32_e32 v143, 31, v142
	v_lshl_add_u64 v[146:147], v[142:143], 2, s[4:5]
	global_load_dword v241, v[146:147], off
	global_load_dword v242, v[146:147], off offset:64
	global_load_dword v243, v[146:147], off offset:128
	global_load_dword v244, v[146:147], off offset:192
	global_load_dword v245, v[146:147], off offset:512
	global_load_dword v246, v[146:147], off offset:576
	global_load_dword v247, v[146:147], off offset:640
	global_load_dword v248, v[146:147], off offset:704
	v_and_b32_e32 v143, 0xff, v0
	v_bfe_u32 v145, v0, 8, 1
	v_lshl_add_u32 v144, s36, 8, v143
	v_add_u32_e32 v144, 0x800, v144
	v_lshlrev_b32_e32 v144, 13, v144
	v_lshl_or_b32 v144, v145, 7, v144
	s_add_u32 s98, s84, 0x2f000000
	s_addc_u32 s99, s85, 0
	global_load_dword v249, v144, s[98:99]
	v_lshl_add_u32 v143, s22, 8, v143
	v_lshlrev_b32_e32 v143, 13, v143
	v_lshl_or_b32 v143, v145, 7, v143
	s_add_u32 s98, s84, 0x5000000
	s_addc_u32 s99, s85, 0
	global_load_dword v249, v143, s[98:99]
	v_lshl_or_b32 v144, s22, 7, v150
	v_ashrrev_i32_e32 v145, 31, v144
	v_mov_b32_e32 v254, 1.0
	v_lshl_add_u64 v[144:145], v[144:145], 1, s[6:7]
	s_andn2_b64 vcc, exec, s[38:39]
	v_mad_i64_i32 v[146:147], s[2:3], v142, s60, v[144:145]
	s_waitcnt vmcnt(9)
	v_fmamk_f32 v251, v241, 0x39800000, v155
	v_rsq_f32_e32 v251, v251
	v_pk_mul_f32 v[126:127], v[118:119], v[126:127]
	v_pk_mul_f32 v[128:129], v[120:121], v[128:129]
	v_pk_mul_f32 v[122:123], v[114:115], v[122:123]
	v_pk_mul_f32 v[124:125], v[116:117], v[124:125]
	v_mul_f32_e32 v250, 0xbfb8aa3b, v251
	v_mul_f32_e32 v252, v251, v251
	v_pk_mul_f32 v[118:119], v[118:119], v[250:251] op_sel_hi:[1,0]
	v_pk_mul_f32 v[120:121], v[120:121], v[250:251] op_sel_hi:[1,0]
	v_pk_mul_f32 v[114:115], v[114:115], v[250:251] op_sel_hi:[1,0]
	v_pk_mul_f32 v[116:117], v[116:117], v[250:251] op_sel_hi:[1,0]
	v_exp_f32_e32 v118, v118
	v_exp_f32_e32 v119, v119
	v_exp_f32_e32 v120, v120
	v_exp_f32_e32 v121, v121
	v_exp_f32_e32 v114, v114
	v_exp_f32_e32 v115, v115
	v_exp_f32_e32 v116, v116
	v_exp_f32_e32 v117, v117
	v_pk_add_f32 v[118:119], v[118:119], v[254:255] op_sel_hi:[1,0]
	v_pk_add_f32 v[120:121], v[120:121], v[254:255] op_sel_hi:[1,0]
	v_pk_add_f32 v[114:115], v[114:115], v[254:255] op_sel_hi:[1,0]
	v_pk_add_f32 v[116:117], v[116:117], v[254:255] op_sel_hi:[1,0]
	v_rcp_f32_e32 v118, v118
	v_rcp_f32_e32 v119, v119
	v_rcp_f32_e32 v120, v120
	v_rcp_f32_e32 v121, v121
	v_rcp_f32_e32 v114, v114
	v_rcp_f32_e32 v115, v115
	v_rcp_f32_e32 v116, v116
	v_rcp_f32_e32 v117, v117
	v_pk_mul_f32 v[118:119], v[118:119], v[252:253] op_sel_hi:[1,0]
	v_pk_mul_f32 v[120:121], v[120:121], v[252:253] op_sel_hi:[1,0]
	v_pk_mul_f32 v[114:115], v[114:115], v[252:253] op_sel_hi:[1,0]
	v_pk_mul_f32 v[116:117], v[116:117], v[252:253] op_sel_hi:[1,0]
	v_pk_mul_f32 v[118:119], v[126:127], v[118:119]
	v_pk_mul_f32 v[120:121], v[128:129], v[120:121]
	v_pk_mul_f32 v[114:115], v[122:123], v[114:115]
	v_pk_mul_f32 v[116:117], v[124:125], v[116:117]
	v_cvt_pk_bf16_f32 v122, v118, v119
	v_cvt_pk_bf16_f32 v123, v120, v121
	v_cvt_pk_bf16_f32 v124, v114, v115
	v_cvt_pk_bf16_f32 v125, v116, v117
	global_store_dwordx4 v[146:147], v[122:125], off
	v_add_u32_e32 v253, 16, v142
	v_mad_i64_i32 v[146:147], s[2:3], v253, s60, v[144:145]
	s_waitcnt vmcnt(8)
	v_fmamk_f32 v251, v242, 0x39800000, v155
	v_rsq_f32_e32 v251, v251
	v_pk_mul_f32 v[110:111], v[102:103], v[110:111]
	v_pk_mul_f32 v[112:113], v[104:105], v[112:113]
	v_pk_mul_f32 v[106:107], v[98:99], v[106:107]
	v_pk_mul_f32 v[108:109], v[100:101], v[108:109]
	v_mul_f32_e32 v250, 0xbfb8aa3b, v251
	v_mul_f32_e32 v252, v251, v251
	v_pk_mul_f32 v[102:103], v[102:103], v[250:251] op_sel_hi:[1,0]
	v_pk_mul_f32 v[104:105], v[104:105], v[250:251] op_sel_hi:[1,0]
	v_pk_mul_f32 v[98:99], v[98:99], v[250:251] op_sel_hi:[1,0]
	v_pk_mul_f32 v[100:101], v[100:101], v[250:251] op_sel_hi:[1,0]
	v_exp_f32_e32 v102, v102
	v_exp_f32_e32 v103, v103
	v_exp_f32_e32 v104, v104
	v_exp_f32_e32 v105, v105
	v_exp_f32_e32 v98, v98
	v_exp_f32_e32 v99, v99
	v_exp_f32_e32 v100, v100
	v_exp_f32_e32 v101, v101
	v_pk_add_f32 v[102:103], v[102:103], v[254:255] op_sel_hi:[1,0]
	v_pk_add_f32 v[104:105], v[104:105], v[254:255] op_sel_hi:[1,0]
	v_pk_add_f32 v[98:99], v[98:99], v[254:255] op_sel_hi:[1,0]
	v_pk_add_f32 v[100:101], v[100:101], v[254:255] op_sel_hi:[1,0]
	v_rcp_f32_e32 v102, v102
	v_rcp_f32_e32 v103, v103
	v_rcp_f32_e32 v104, v104
	v_rcp_f32_e32 v105, v105
	v_rcp_f32_e32 v98, v98
	v_rcp_f32_e32 v99, v99
	v_rcp_f32_e32 v100, v100
	v_rcp_f32_e32 v101, v101
	v_pk_mul_f32 v[102:103], v[102:103], v[252:253] op_sel_hi:[1,0]
	v_pk_mul_f32 v[104:105], v[104:105], v[252:253] op_sel_hi:[1,0]
	v_pk_mul_f32 v[98:99], v[98:99], v[252:253] op_sel_hi:[1,0]
	v_pk_mul_f32 v[100:101], v[100:101], v[252:253] op_sel_hi:[1,0]
	v_pk_mul_f32 v[102:103], v[110:111], v[102:103]
	v_pk_mul_f32 v[104:105], v[112:113], v[104:105]
	v_pk_mul_f32 v[98:99], v[106:107], v[98:99]
	v_pk_mul_f32 v[100:101], v[108:109], v[100:101]
	v_cvt_pk_bf16_f32 v106, v102, v103
	v_cvt_pk_bf16_f32 v107, v104, v105
	v_cvt_pk_bf16_f32 v108, v98, v99
	v_cvt_pk_bf16_f32 v109, v100, v101
	global_store_dwordx4 v[146:147], v[106:109], off
	v_add_u32_e32 v253, 32, v142
	v_mad_i64_i32 v[146:147], s[2:3], v253, s60, v[144:145]
	s_waitcnt vmcnt(7)
	v_fmamk_f32 v251, v243, 0x39800000, v155
	v_rsq_f32_e32 v251, v251
	v_pk_mul_f32 v[94:95], v[86:87], v[94:95]
	v_pk_mul_f32 v[96:97], v[88:89], v[96:97]
	v_pk_mul_f32 v[90:91], v[82:83], v[90:91]
	v_pk_mul_f32 v[92:93], v[84:85], v[92:93]
	v_mul_f32_e32 v250, 0xbfb8aa3b, v251
	v_mul_f32_e32 v252, v251, v251
	v_pk_mul_f32 v[86:87], v[86:87], v[250:251] op_sel_hi:[1,0]
	v_pk_mul_f32 v[88:89], v[88:89], v[250:251] op_sel_hi:[1,0]
	v_pk_mul_f32 v[82:83], v[82:83], v[250:251] op_sel_hi:[1,0]
	v_pk_mul_f32 v[84:85], v[84:85], v[250:251] op_sel_hi:[1,0]
	v_exp_f32_e32 v86, v86
	v_exp_f32_e32 v87, v87
	v_exp_f32_e32 v88, v88
	v_exp_f32_e32 v89, v89
	v_exp_f32_e32 v82, v82
	v_exp_f32_e32 v83, v83
	v_exp_f32_e32 v84, v84
	v_exp_f32_e32 v85, v85
	v_pk_add_f32 v[86:87], v[86:87], v[254:255] op_sel_hi:[1,0]
	v_pk_add_f32 v[88:89], v[88:89], v[254:255] op_sel_hi:[1,0]
	v_pk_add_f32 v[82:83], v[82:83], v[254:255] op_sel_hi:[1,0]
	v_pk_add_f32 v[84:85], v[84:85], v[254:255] op_sel_hi:[1,0]
	v_rcp_f32_e32 v86, v86
	v_rcp_f32_e32 v87, v87
	v_rcp_f32_e32 v88, v88
	v_rcp_f32_e32 v89, v89
	v_rcp_f32_e32 v82, v82
	v_rcp_f32_e32 v83, v83
	v_rcp_f32_e32 v84, v84
	v_rcp_f32_e32 v85, v85
	v_pk_mul_f32 v[86:87], v[86:87], v[252:253] op_sel_hi:[1,0]
	v_pk_mul_f32 v[88:89], v[88:89], v[252:253] op_sel_hi:[1,0]
	v_pk_mul_f32 v[82:83], v[82:83], v[252:253] op_sel_hi:[1,0]
	v_pk_mul_f32 v[84:85], v[84:85], v[252:253] op_sel_hi:[1,0]
	v_pk_mul_f32 v[86:87], v[94:95], v[86:87]
	v_pk_mul_f32 v[88:89], v[96:97], v[88:89]
	v_pk_mul_f32 v[82:83], v[90:91], v[82:83]
	v_pk_mul_f32 v[84:85], v[92:93], v[84:85]
	v_cvt_pk_bf16_f32 v90, v86, v87
	v_cvt_pk_bf16_f32 v91, v88, v89
	v_cvt_pk_bf16_f32 v92, v82, v83
	v_cvt_pk_bf16_f32 v93, v84, v85
	global_store_dwordx4 v[146:147], v[90:93], off
	v_add_u32_e32 v253, 48, v142
	v_mad_i64_i32 v[146:147], s[2:3], v253, s60, v[144:145]
	s_waitcnt vmcnt(6)
	v_fmamk_f32 v251, v244, 0x39800000, v155
	v_rsq_f32_e32 v251, v251
	v_pk_mul_f32 v[78:79], v[70:71], v[78:79]
	v_pk_mul_f32 v[80:81], v[72:73], v[80:81]
	v_pk_mul_f32 v[74:75], v[66:67], v[74:75]
	v_pk_mul_f32 v[76:77], v[68:69], v[76:77]
	v_mul_f32_e32 v250, 0xbfb8aa3b, v251
	v_mul_f32_e32 v252, v251, v251
	v_pk_mul_f32 v[70:71], v[70:71], v[250:251] op_sel_hi:[1,0]
	v_pk_mul_f32 v[72:73], v[72:73], v[250:251] op_sel_hi:[1,0]
	v_pk_mul_f32 v[66:67], v[66:67], v[250:251] op_sel_hi:[1,0]
	v_pk_mul_f32 v[68:69], v[68:69], v[250:251] op_sel_hi:[1,0]
	v_exp_f32_e32 v70, v70
	v_exp_f32_e32 v71, v71
	v_exp_f32_e32 v72, v72
	v_exp_f32_e32 v73, v73
	v_exp_f32_e32 v66, v66
	v_exp_f32_e32 v67, v67
	v_exp_f32_e32 v68, v68
	v_exp_f32_e32 v69, v69
	v_pk_add_f32 v[70:71], v[70:71], v[254:255] op_sel_hi:[1,0]
	v_pk_add_f32 v[72:73], v[72:73], v[254:255] op_sel_hi:[1,0]
	v_pk_add_f32 v[66:67], v[66:67], v[254:255] op_sel_hi:[1,0]
	v_pk_add_f32 v[68:69], v[68:69], v[254:255] op_sel_hi:[1,0]
	v_rcp_f32_e32 v70, v70
	v_rcp_f32_e32 v71, v71
	v_rcp_f32_e32 v72, v72
	v_rcp_f32_e32 v73, v73
	v_rcp_f32_e32 v66, v66
	v_rcp_f32_e32 v67, v67
	v_rcp_f32_e32 v68, v68
	v_rcp_f32_e32 v69, v69
	v_pk_mul_f32 v[70:71], v[70:71], v[252:253] op_sel_hi:[1,0]
	v_pk_mul_f32 v[72:73], v[72:73], v[252:253] op_sel_hi:[1,0]
	v_pk_mul_f32 v[66:67], v[66:67], v[252:253] op_sel_hi:[1,0]
	v_pk_mul_f32 v[68:69], v[68:69], v[252:253] op_sel_hi:[1,0]
	v_pk_mul_f32 v[70:71], v[78:79], v[70:71]
	v_pk_mul_f32 v[72:73], v[80:81], v[72:73]
	v_pk_mul_f32 v[66:67], v[74:75], v[66:67]
	v_pk_mul_f32 v[68:69], v[76:77], v[68:69]
	v_cvt_pk_bf16_f32 v74, v70, v71
	v_cvt_pk_bf16_f32 v75, v72, v73
	v_cvt_pk_bf16_f32 v76, v66, v67
	v_cvt_pk_bf16_f32 v77, v68, v69
	global_store_dwordx4 v[146:147], v[74:77], off
	v_add_u32_e32 v253, 128, v142
	v_mad_i64_i32 v[146:147], s[2:3], v253, s60, v[144:145]
	s_waitcnt vmcnt(5)
	v_fmamk_f32 v251, v245, 0x39800000, v155
	v_rsq_f32_e32 v251, v251
	v_pk_mul_f32 v[62:63], v[54:55], v[62:63]
	v_pk_mul_f32 v[64:65], v[56:57], v[64:65]
	v_pk_mul_f32 v[58:59], v[50:51], v[58:59]
	v_pk_mul_f32 v[60:61], v[52:53], v[60:61]
	v_mul_f32_e32 v250, 0xbfb8aa3b, v251
	v_mul_f32_e32 v252, v251, v251
	v_pk_mul_f32 v[54:55], v[54:55], v[250:251] op_sel_hi:[1,0]
	v_pk_mul_f32 v[56:57], v[56:57], v[250:251] op_sel_hi:[1,0]
	v_pk_mul_f32 v[50:51], v[50:51], v[250:251] op_sel_hi:[1,0]
	v_pk_mul_f32 v[52:53], v[52:53], v[250:251] op_sel_hi:[1,0]
	v_exp_f32_e32 v54, v54
	v_exp_f32_e32 v55, v55
	v_exp_f32_e32 v56, v56
	v_exp_f32_e32 v57, v57
	v_exp_f32_e32 v50, v50
	v_exp_f32_e32 v51, v51
	v_exp_f32_e32 v52, v52
	v_exp_f32_e32 v53, v53
	v_pk_add_f32 v[54:55], v[54:55], v[254:255] op_sel_hi:[1,0]
	v_pk_add_f32 v[56:57], v[56:57], v[254:255] op_sel_hi:[1,0]
	v_pk_add_f32 v[50:51], v[50:51], v[254:255] op_sel_hi:[1,0]
	v_pk_add_f32 v[52:53], v[52:53], v[254:255] op_sel_hi:[1,0]
	v_rcp_f32_e32 v54, v54
	v_rcp_f32_e32 v55, v55
	v_rcp_f32_e32 v56, v56
	v_rcp_f32_e32 v57, v57
	v_rcp_f32_e32 v50, v50
	v_rcp_f32_e32 v51, v51
	v_rcp_f32_e32 v52, v52
	v_rcp_f32_e32 v53, v53
	v_pk_mul_f32 v[54:55], v[54:55], v[252:253] op_sel_hi:[1,0]
	v_pk_mul_f32 v[56:57], v[56:57], v[252:253] op_sel_hi:[1,0]
	v_pk_mul_f32 v[50:51], v[50:51], v[252:253] op_sel_hi:[1,0]
	v_pk_mul_f32 v[52:53], v[52:53], v[252:253] op_sel_hi:[1,0]
	v_pk_mul_f32 v[54:55], v[62:63], v[54:55]
	v_pk_mul_f32 v[56:57], v[64:65], v[56:57]
	v_pk_mul_f32 v[50:51], v[58:59], v[50:51]
	v_pk_mul_f32 v[52:53], v[60:61], v[52:53]
	v_cvt_pk_bf16_f32 v58, v54, v55
	v_cvt_pk_bf16_f32 v59, v56, v57
	v_cvt_pk_bf16_f32 v60, v50, v51
	v_cvt_pk_bf16_f32 v61, v52, v53
	global_store_dwordx4 v[146:147], v[58:61], off
	v_add_u32_e32 v253, 144, v142
	v_mad_i64_i32 v[146:147], s[2:3], v253, s60, v[144:145]
	s_waitcnt vmcnt(4)
	v_fmamk_f32 v251, v246, 0x39800000, v155
	v_rsq_f32_e32 v251, v251
	v_pk_mul_f32 v[46:47], v[38:39], v[46:47]
	v_pk_mul_f32 v[48:49], v[40:41], v[48:49]
	v_pk_mul_f32 v[42:43], v[34:35], v[42:43]
	v_pk_mul_f32 v[44:45], v[36:37], v[44:45]
	v_mul_f32_e32 v250, 0xbfb8aa3b, v251
	v_mul_f32_e32 v252, v251, v251
	v_pk_mul_f32 v[38:39], v[38:39], v[250:251] op_sel_hi:[1,0]
	v_pk_mul_f32 v[40:41], v[40:41], v[250:251] op_sel_hi:[1,0]
	v_pk_mul_f32 v[34:35], v[34:35], v[250:251] op_sel_hi:[1,0]
	v_pk_mul_f32 v[36:37], v[36:37], v[250:251] op_sel_hi:[1,0]
	v_exp_f32_e32 v38, v38
	v_exp_f32_e32 v39, v39
	v_exp_f32_e32 v40, v40
	v_exp_f32_e32 v41, v41
	v_exp_f32_e32 v34, v34
	v_exp_f32_e32 v35, v35
	v_exp_f32_e32 v36, v36
	v_exp_f32_e32 v37, v37
	v_pk_add_f32 v[38:39], v[38:39], v[254:255] op_sel_hi:[1,0]
	v_pk_add_f32 v[40:41], v[40:41], v[254:255] op_sel_hi:[1,0]
	v_pk_add_f32 v[34:35], v[34:35], v[254:255] op_sel_hi:[1,0]
	v_pk_add_f32 v[36:37], v[36:37], v[254:255] op_sel_hi:[1,0]
	v_rcp_f32_e32 v38, v38
	v_rcp_f32_e32 v39, v39
	v_rcp_f32_e32 v40, v40
	v_rcp_f32_e32 v41, v41
	v_rcp_f32_e32 v34, v34
	v_rcp_f32_e32 v35, v35
	v_rcp_f32_e32 v36, v36
	v_rcp_f32_e32 v37, v37
	v_pk_mul_f32 v[38:39], v[38:39], v[252:253] op_sel_hi:[1,0]
	v_pk_mul_f32 v[40:41], v[40:41], v[252:253] op_sel_hi:[1,0]
	v_pk_mul_f32 v[34:35], v[34:35], v[252:253] op_sel_hi:[1,0]
	v_pk_mul_f32 v[36:37], v[36:37], v[252:253] op_sel_hi:[1,0]
	v_pk_mul_f32 v[38:39], v[46:47], v[38:39]
	v_pk_mul_f32 v[40:41], v[48:49], v[40:41]
	v_pk_mul_f32 v[34:35], v[42:43], v[34:35]
	v_pk_mul_f32 v[36:37], v[44:45], v[36:37]
	v_cvt_pk_bf16_f32 v42, v38, v39
	v_cvt_pk_bf16_f32 v43, v40, v41
	v_cvt_pk_bf16_f32 v44, v34, v35
	v_cvt_pk_bf16_f32 v45, v36, v37
	global_store_dwordx4 v[146:147], v[42:45], off
	v_add_u32_e32 v253, 160, v142
	v_mad_i64_i32 v[146:147], s[2:3], v253, s60, v[144:145]
	s_waitcnt vmcnt(3)
	v_fmamk_f32 v251, v247, 0x39800000, v155
	v_rsq_f32_e32 v251, v251
	v_pk_mul_f32 v[30:31], v[22:23], v[30:31]
	v_pk_mul_f32 v[32:33], v[24:25], v[32:33]
	v_pk_mul_f32 v[26:27], v[18:19], v[26:27]
	v_pk_mul_f32 v[28:29], v[20:21], v[28:29]
	v_mul_f32_e32 v250, 0xbfb8aa3b, v251
	v_mul_f32_e32 v252, v251, v251
	v_pk_mul_f32 v[22:23], v[22:23], v[250:251] op_sel_hi:[1,0]
	v_pk_mul_f32 v[24:25], v[24:25], v[250:251] op_sel_hi:[1,0]
	v_pk_mul_f32 v[18:19], v[18:19], v[250:251] op_sel_hi:[1,0]
	v_pk_mul_f32 v[20:21], v[20:21], v[250:251] op_sel_hi:[1,0]
	v_exp_f32_e32 v22, v22
	v_exp_f32_e32 v23, v23
	v_exp_f32_e32 v24, v24
	v_exp_f32_e32 v25, v25
	v_exp_f32_e32 v18, v18
	v_exp_f32_e32 v19, v19
	v_exp_f32_e32 v20, v20
	v_exp_f32_e32 v21, v21
	v_pk_add_f32 v[22:23], v[22:23], v[254:255] op_sel_hi:[1,0]
	v_pk_add_f32 v[24:25], v[24:25], v[254:255] op_sel_hi:[1,0]
	v_pk_add_f32 v[18:19], v[18:19], v[254:255] op_sel_hi:[1,0]
	v_pk_add_f32 v[20:21], v[20:21], v[254:255] op_sel_hi:[1,0]
	v_rcp_f32_e32 v22, v22
	v_rcp_f32_e32 v23, v23
	v_rcp_f32_e32 v24, v24
	v_rcp_f32_e32 v25, v25
	v_rcp_f32_e32 v18, v18
	v_rcp_f32_e32 v19, v19
	v_rcp_f32_e32 v20, v20
	v_rcp_f32_e32 v21, v21
	v_pk_mul_f32 v[22:23], v[22:23], v[252:253] op_sel_hi:[1,0]
	v_pk_mul_f32 v[24:25], v[24:25], v[252:253] op_sel_hi:[1,0]
	v_pk_mul_f32 v[18:19], v[18:19], v[252:253] op_sel_hi:[1,0]
	v_pk_mul_f32 v[20:21], v[20:21], v[252:253] op_sel_hi:[1,0]
	v_pk_mul_f32 v[22:23], v[30:31], v[22:23]
	v_pk_mul_f32 v[24:25], v[32:33], v[24:25]
	v_pk_mul_f32 v[18:19], v[26:27], v[18:19]
	v_pk_mul_f32 v[20:21], v[28:29], v[20:21]
	v_cvt_pk_bf16_f32 v26, v22, v23
	v_cvt_pk_bf16_f32 v27, v24, v25
	v_cvt_pk_bf16_f32 v28, v18, v19
	v_cvt_pk_bf16_f32 v29, v20, v21
	global_store_dwordx4 v[146:147], v[26:29], off
	v_add_u32_e32 v253, 176, v142
	v_mad_i64_i32 v[146:147], s[2:3], v253, s60, v[144:145]
	s_mov_b64 s[2:3], -1
	s_waitcnt vmcnt(2)
	v_fmamk_f32 v251, v248, 0x39800000, v155
	v_rsq_f32_e32 v251, v251
	v_pk_mul_f32 v[14:15], v[6:7], v[14:15]
	v_pk_mul_f32 v[16:17], v[8:9], v[16:17]
	v_pk_mul_f32 v[10:11], v[2:3], v[10:11]
	v_pk_mul_f32 v[12:13], v[4:5], v[12:13]
	v_mul_f32_e32 v250, 0xbfb8aa3b, v251
	v_mul_f32_e32 v252, v251, v251
	v_pk_mul_f32 v[6:7], v[6:7], v[250:251] op_sel_hi:[1,0]
	v_pk_mul_f32 v[8:9], v[8:9], v[250:251] op_sel_hi:[1,0]
	v_pk_mul_f32 v[2:3], v[2:3], v[250:251] op_sel_hi:[1,0]
	v_pk_mul_f32 v[4:5], v[4:5], v[250:251] op_sel_hi:[1,0]
	v_exp_f32_e32 v6, v6
	v_exp_f32_e32 v7, v7
	v_exp_f32_e32 v8, v8
	v_exp_f32_e32 v9, v9
	v_exp_f32_e32 v2, v2
	v_exp_f32_e32 v3, v3
	v_exp_f32_e32 v4, v4
	v_exp_f32_e32 v5, v5
	v_pk_add_f32 v[6:7], v[6:7], v[254:255] op_sel_hi:[1,0]
	v_pk_add_f32 v[8:9], v[8:9], v[254:255] op_sel_hi:[1,0]
	v_pk_add_f32 v[2:3], v[2:3], v[254:255] op_sel_hi:[1,0]
	v_pk_add_f32 v[4:5], v[4:5], v[254:255] op_sel_hi:[1,0]
	v_rcp_f32_e32 v6, v6
	v_rcp_f32_e32 v7, v7
	v_rcp_f32_e32 v8, v8
	v_rcp_f32_e32 v9, v9
	v_rcp_f32_e32 v2, v2
	v_rcp_f32_e32 v3, v3
	v_rcp_f32_e32 v4, v4
	v_rcp_f32_e32 v5, v5
	v_pk_mul_f32 v[6:7], v[6:7], v[252:253] op_sel_hi:[1,0]
	v_pk_mul_f32 v[8:9], v[8:9], v[252:253] op_sel_hi:[1,0]
	v_pk_mul_f32 v[2:3], v[2:3], v[252:253] op_sel_hi:[1,0]
	v_pk_mul_f32 v[4:5], v[4:5], v[252:253] op_sel_hi:[1,0]
	v_pk_mul_f32 v[6:7], v[14:15], v[6:7]
	v_pk_mul_f32 v[8:9], v[16:17], v[8:9]
	v_pk_mul_f32 v[2:3], v[10:11], v[2:3]
	v_pk_mul_f32 v[4:5], v[12:13], v[4:5]
	v_cvt_pk_bf16_f32 v10, v6, v7
	v_cvt_pk_bf16_f32 v11, v8, v9
	v_cvt_pk_bf16_f32 v12, v2, v3
	v_cvt_pk_bf16_f32 v13, v4, v5
	global_store_dwordx4 v[146:147], v[10:13], off
	s_cbranch_vccnz .LBB0_401
	s_andn2_b64 vcc, exec, s[0:1]
	s_cbranch_vccnz .LBB0_400
	s_barrier
	s_branch .LBB0_400

.LBB0_1336:
	v_lshl_add_u32 v142, s22, 8, v153
	v_ashrrev_i32_e32 v143, 31, v142
	v_lshl_add_u64 v[146:147], v[142:143], 2, s[4:5]
	global_load_dword v241, v[146:147], off
	global_load_dword v242, v[146:147], off offset:64
	global_load_dword v243, v[146:147], off offset:128
	global_load_dword v244, v[146:147], off offset:192
	global_load_dword v245, v[146:147], off offset:512
	global_load_dword v246, v[146:147], off offset:576
	global_load_dword v247, v[146:147], off offset:640
	global_load_dword v248, v[146:147], off offset:704
	v_and_b32_e32 v143, 0xff, v0
	v_bfe_u32 v145, v0, 8, 1
	v_lshl_add_u32 v144, s22, 8, v143
	v_add_u32_e32 v144, 0x800, v144
	v_lshlrev_b32_e32 v144, 13, v144
	v_lshl_or_b32 v144, v145, 7, v144
	s_add_u32 s98, s84, 0x2f000000
	s_addc_u32 s99, s85, 0
	global_load_dword v249, v144, s[98:99]
	v_lshl_add_u32 v143, s18, 8, v143
	v_lshlrev_b32_e32 v143, 13, v143
	v_lshl_or_b32 v143, v145, 7, v143
	s_add_u32 s98, s84, 0xfc00000
	s_addc_u32 s99, s85, 0
	global_load_dword v249, v143, s[98:99]
	v_lshl_or_b32 v144, s18, 7, v158
	v_ashrrev_i32_e32 v145, 31, v144
	v_mov_b32_e32 v254, 1.0
	v_lshl_add_u64 v[144:145], v[144:145], 1, s[6:7]
	s_andn2_b64 vcc, exec, s[26:27]
	v_mad_i64_i32 v[146:147], s[2:3], v142, s57, v[144:145]
	s_waitcnt vmcnt(9)
	v_fmamk_f32 v251, v241, 0x39800000, v162
	v_rsq_f32_e32 v251, v251
	v_pk_mul_f32 v[126:127], v[118:119], v[126:127]
	v_pk_mul_f32 v[128:129], v[120:121], v[128:129]
	v_pk_mul_f32 v[122:123], v[114:115], v[122:123]
	v_pk_mul_f32 v[124:125], v[116:117], v[124:125]
	v_mul_f32_e32 v250, 0xbfb8aa3b, v251
	v_mul_f32_e32 v252, v251, v251
	v_pk_mul_f32 v[118:119], v[118:119], v[250:251] op_sel_hi:[1,0]
	v_pk_mul_f32 v[120:121], v[120:121], v[250:251] op_sel_hi:[1,0]
	v_pk_mul_f32 v[114:115], v[114:115], v[250:251] op_sel_hi:[1,0]
	v_pk_mul_f32 v[116:117], v[116:117], v[250:251] op_sel_hi:[1,0]
	v_exp_f32_e32 v118, v118
	v_exp_f32_e32 v119, v119
	v_exp_f32_e32 v120, v120
	v_exp_f32_e32 v121, v121
	v_exp_f32_e32 v114, v114
	v_exp_f32_e32 v115, v115
	v_exp_f32_e32 v116, v116
	v_exp_f32_e32 v117, v117
	v_pk_add_f32 v[118:119], v[118:119], v[254:255] op_sel_hi:[1,0]
	v_pk_add_f32 v[120:121], v[120:121], v[254:255] op_sel_hi:[1,0]
	v_pk_add_f32 v[114:115], v[114:115], v[254:255] op_sel_hi:[1,0]
	v_pk_add_f32 v[116:117], v[116:117], v[254:255] op_sel_hi:[1,0]
	v_rcp_f32_e32 v118, v118
	v_rcp_f32_e32 v119, v119
	v_rcp_f32_e32 v120, v120
	v_rcp_f32_e32 v121, v121
	v_rcp_f32_e32 v114, v114
	v_rcp_f32_e32 v115, v115
	v_rcp_f32_e32 v116, v116
	v_rcp_f32_e32 v117, v117
	v_pk_mul_f32 v[118:119], v[118:119], v[252:253] op_sel_hi:[1,0]
	v_pk_mul_f32 v[120:121], v[120:121], v[252:253] op_sel_hi:[1,0]
	v_pk_mul_f32 v[114:115], v[114:115], v[252:253] op_sel_hi:[1,0]
	v_pk_mul_f32 v[116:117], v[116:117], v[252:253] op_sel_hi:[1,0]
	v_pk_mul_f32 v[118:119], v[126:127], v[118:119]
	v_pk_mul_f32 v[120:121], v[128:129], v[120:121]
	v_pk_mul_f32 v[114:115], v[122:123], v[114:115]
	v_pk_mul_f32 v[116:117], v[124:125], v[116:117]
	v_cvt_pk_bf16_f32 v122, v118, v119
	v_cvt_pk_bf16_f32 v123, v120, v121
	v_cvt_pk_bf16_f32 v124, v114, v115
	v_cvt_pk_bf16_f32 v125, v116, v117
	global_store_dwordx4 v[146:147], v[122:125], off
	v_add_u32_e32 v253, 16, v142
	v_mad_i64_i32 v[146:147], s[2:3], v253, s57, v[144:145]
	s_waitcnt vmcnt(8)
	v_fmamk_f32 v251, v242, 0x39800000, v162
	v_rsq_f32_e32 v251, v251
	v_pk_mul_f32 v[110:111], v[102:103], v[110:111]
	v_pk_mul_f32 v[112:113], v[104:105], v[112:113]
	v_pk_mul_f32 v[106:107], v[98:99], v[106:107]
	v_pk_mul_f32 v[108:109], v[100:101], v[108:109]
	v_mul_f32_e32 v250, 0xbfb8aa3b, v251
	v_mul_f32_e32 v252, v251, v251
	v_pk_mul_f32 v[102:103], v[102:103], v[250:251] op_sel_hi:[1,0]
	v_pk_mul_f32 v[104:105], v[104:105], v[250:251] op_sel_hi:[1,0]
	v_pk_mul_f32 v[98:99], v[98:99], v[250:251] op_sel_hi:[1,0]
	v_pk_mul_f32 v[100:101], v[100:101], v[250:251] op_sel_hi:[1,0]
	v_exp_f32_e32 v102, v102
	v_exp_f32_e32 v103, v103
	v_exp_f32_e32 v104, v104
	v_exp_f32_e32 v105, v105
	v_exp_f32_e32 v98, v98
	v_exp_f32_e32 v99, v99
	v_exp_f32_e32 v100, v100
	v_exp_f32_e32 v101, v101
	v_pk_add_f32 v[102:103], v[102:103], v[254:255] op_sel_hi:[1,0]
	v_pk_add_f32 v[104:105], v[104:105], v[254:255] op_sel_hi:[1,0]
	v_pk_add_f32 v[98:99], v[98:99], v[254:255] op_sel_hi:[1,0]
	v_pk_add_f32 v[100:101], v[100:101], v[254:255] op_sel_hi:[1,0]
	v_rcp_f32_e32 v102, v102
	v_rcp_f32_e32 v103, v103
	v_rcp_f32_e32 v104, v104
	v_rcp_f32_e32 v105, v105
	v_rcp_f32_e32 v98, v98
	v_rcp_f32_e32 v99, v99
	v_rcp_f32_e32 v100, v100
	v_rcp_f32_e32 v101, v101
	v_pk_mul_f32 v[102:103], v[102:103], v[252:253] op_sel_hi:[1,0]
	v_pk_mul_f32 v[104:105], v[104:105], v[252:253] op_sel_hi:[1,0]
	v_pk_mul_f32 v[98:99], v[98:99], v[252:253] op_sel_hi:[1,0]
	v_pk_mul_f32 v[100:101], v[100:101], v[252:253] op_sel_hi:[1,0]
	v_pk_mul_f32 v[102:103], v[110:111], v[102:103]
	v_pk_mul_f32 v[104:105], v[112:113], v[104:105]
	v_pk_mul_f32 v[98:99], v[106:107], v[98:99]
	v_pk_mul_f32 v[100:101], v[108:109], v[100:101]
	v_cvt_pk_bf16_f32 v106, v102, v103
	v_cvt_pk_bf16_f32 v107, v104, v105
	v_cvt_pk_bf16_f32 v108, v98, v99
	v_cvt_pk_bf16_f32 v109, v100, v101
	global_store_dwordx4 v[146:147], v[106:109], off
	v_add_u32_e32 v253, 32, v142
	v_mad_i64_i32 v[146:147], s[2:3], v253, s57, v[144:145]
	s_waitcnt vmcnt(7)
	v_fmamk_f32 v251, v243, 0x39800000, v162
	v_rsq_f32_e32 v251, v251
	v_pk_mul_f32 v[94:95], v[86:87], v[94:95]
	v_pk_mul_f32 v[96:97], v[88:89], v[96:97]
	v_pk_mul_f32 v[90:91], v[82:83], v[90:91]
	v_pk_mul_f32 v[92:93], v[84:85], v[92:93]
	v_mul_f32_e32 v250, 0xbfb8aa3b, v251
	v_mul_f32_e32 v252, v251, v251
	v_pk_mul_f32 v[86:87], v[86:87], v[250:251] op_sel_hi:[1,0]
	v_pk_mul_f32 v[88:89], v[88:89], v[250:251] op_sel_hi:[1,0]
	v_pk_mul_f32 v[82:83], v[82:83], v[250:251] op_sel_hi:[1,0]
	v_pk_mul_f32 v[84:85], v[84:85], v[250:251] op_sel_hi:[1,0]
	v_exp_f32_e32 v86, v86
	v_exp_f32_e32 v87, v87
	v_exp_f32_e32 v88, v88
	v_exp_f32_e32 v89, v89
	v_exp_f32_e32 v82, v82
	v_exp_f32_e32 v83, v83
	v_exp_f32_e32 v84, v84
	v_exp_f32_e32 v85, v85
	v_pk_add_f32 v[86:87], v[86:87], v[254:255] op_sel_hi:[1,0]
	v_pk_add_f32 v[88:89], v[88:89], v[254:255] op_sel_hi:[1,0]
	v_pk_add_f32 v[82:83], v[82:83], v[254:255] op_sel_hi:[1,0]
	v_pk_add_f32 v[84:85], v[84:85], v[254:255] op_sel_hi:[1,0]
	v_rcp_f32_e32 v86, v86
	v_rcp_f32_e32 v87, v87
	v_rcp_f32_e32 v88, v88
	v_rcp_f32_e32 v89, v89
	v_rcp_f32_e32 v82, v82
	v_rcp_f32_e32 v83, v83
	v_rcp_f32_e32 v84, v84
	v_rcp_f32_e32 v85, v85
	v_pk_mul_f32 v[86:87], v[86:87], v[252:253] op_sel_hi:[1,0]
	v_pk_mul_f32 v[88:89], v[88:89], v[252:253] op_sel_hi:[1,0]
	v_pk_mul_f32 v[82:83], v[82:83], v[252:253] op_sel_hi:[1,0]
	v_pk_mul_f32 v[84:85], v[84:85], v[252:253] op_sel_hi:[1,0]
	v_pk_mul_f32 v[86:87], v[94:95], v[86:87]
	v_pk_mul_f32 v[88:89], v[96:97], v[88:89]
	v_pk_mul_f32 v[82:83], v[90:91], v[82:83]
	v_pk_mul_f32 v[84:85], v[92:93], v[84:85]
	v_cvt_pk_bf16_f32 v90, v86, v87
	v_cvt_pk_bf16_f32 v91, v88, v89
	v_cvt_pk_bf16_f32 v92, v82, v83
	v_cvt_pk_bf16_f32 v93, v84, v85
	global_store_dwordx4 v[146:147], v[90:93], off
	v_add_u32_e32 v253, 48, v142
	v_mad_i64_i32 v[146:147], s[2:3], v253, s57, v[144:145]
	s_waitcnt vmcnt(6)
	v_fmamk_f32 v251, v244, 0x39800000, v162
	v_rsq_f32_e32 v251, v251
	v_pk_mul_f32 v[78:79], v[70:71], v[78:79]
	v_pk_mul_f32 v[80:81], v[72:73], v[80:81]
	v_pk_mul_f32 v[74:75], v[66:67], v[74:75]
	v_pk_mul_f32 v[76:77], v[68:69], v[76:77]
	v_mul_f32_e32 v250, 0xbfb8aa3b, v251
	v_mul_f32_e32 v252, v251, v251
	v_pk_mul_f32 v[70:71], v[70:71], v[250:251] op_sel_hi:[1,0]
	v_pk_mul_f32 v[72:73], v[72:73], v[250:251] op_sel_hi:[1,0]
	v_pk_mul_f32 v[66:67], v[66:67], v[250:251] op_sel_hi:[1,0]
	v_pk_mul_f32 v[68:69], v[68:69], v[250:251] op_sel_hi:[1,0]
	v_exp_f32_e32 v70, v70
	v_exp_f32_e32 v71, v71
	v_exp_f32_e32 v72, v72
	v_exp_f32_e32 v73, v73
	v_exp_f32_e32 v66, v66
	v_exp_f32_e32 v67, v67
	v_exp_f32_e32 v68, v68
	v_exp_f32_e32 v69, v69
	v_pk_add_f32 v[70:71], v[70:71], v[254:255] op_sel_hi:[1,0]
	v_pk_add_f32 v[72:73], v[72:73], v[254:255] op_sel_hi:[1,0]
	v_pk_add_f32 v[66:67], v[66:67], v[254:255] op_sel_hi:[1,0]
	v_pk_add_f32 v[68:69], v[68:69], v[254:255] op_sel_hi:[1,0]
	v_rcp_f32_e32 v70, v70
	v_rcp_f32_e32 v71, v71
	v_rcp_f32_e32 v72, v72
	v_rcp_f32_e32 v73, v73
	v_rcp_f32_e32 v66, v66
	v_rcp_f32_e32 v67, v67
	v_rcp_f32_e32 v68, v68
	v_rcp_f32_e32 v69, v69
	v_pk_mul_f32 v[70:71], v[70:71], v[252:253] op_sel_hi:[1,0]
	v_pk_mul_f32 v[72:73], v[72:73], v[252:253] op_sel_hi:[1,0]
	v_pk_mul_f32 v[66:67], v[66:67], v[252:253] op_sel_hi:[1,0]
	v_pk_mul_f32 v[68:69], v[68:69], v[252:253] op_sel_hi:[1,0]
	v_pk_mul_f32 v[70:71], v[78:79], v[70:71]
	v_pk_mul_f32 v[72:73], v[80:81], v[72:73]
	v_pk_mul_f32 v[66:67], v[74:75], v[66:67]
	v_pk_mul_f32 v[68:69], v[76:77], v[68:69]
	v_cvt_pk_bf16_f32 v74, v70, v71
	v_cvt_pk_bf16_f32 v75, v72, v73
	v_cvt_pk_bf16_f32 v76, v66, v67
	v_cvt_pk_bf16_f32 v77, v68, v69
	global_store_dwordx4 v[146:147], v[74:77], off
	v_add_u32_e32 v253, 128, v142
	v_mad_i64_i32 v[146:147], s[2:3], v253, s57, v[144:145]
	s_waitcnt vmcnt(5)
	v_fmamk_f32 v251, v245, 0x39800000, v162
	v_rsq_f32_e32 v251, v251
	v_pk_mul_f32 v[62:63], v[54:55], v[62:63]
	v_pk_mul_f32 v[64:65], v[56:57], v[64:65]
	v_pk_mul_f32 v[58:59], v[50:51], v[58:59]
	v_pk_mul_f32 v[60:61], v[52:53], v[60:61]
	v_mul_f32_e32 v250, 0xbfb8aa3b, v251
	v_mul_f32_e32 v252, v251, v251
	v_pk_mul_f32 v[54:55], v[54:55], v[250:251] op_sel_hi:[1,0]
	v_pk_mul_f32 v[56:57], v[56:57], v[250:251] op_sel_hi:[1,0]
	v_pk_mul_f32 v[50:51], v[50:51], v[250:251] op_sel_hi:[1,0]
	v_pk_mul_f32 v[52:53], v[52:53], v[250:251] op_sel_hi:[1,0]
	v_exp_f32_e32 v54, v54
	v_exp_f32_e32 v55, v55
	v_exp_f32_e32 v56, v56
	v_exp_f32_e32 v57, v57
	v_exp_f32_e32 v50, v50
	v_exp_f32_e32 v51, v51
	v_exp_f32_e32 v52, v52
	v_exp_f32_e32 v53, v53
	v_pk_add_f32 v[54:55], v[54:55], v[254:255] op_sel_hi:[1,0]
	v_pk_add_f32 v[56:57], v[56:57], v[254:255] op_sel_hi:[1,0]
	v_pk_add_f32 v[50:51], v[50:51], v[254:255] op_sel_hi:[1,0]
	v_pk_add_f32 v[52:53], v[52:53], v[254:255] op_sel_hi:[1,0]
	v_rcp_f32_e32 v54, v54
	v_rcp_f32_e32 v55, v55
	v_rcp_f32_e32 v56, v56
	v_rcp_f32_e32 v57, v57
	v_rcp_f32_e32 v50, v50
	v_rcp_f32_e32 v51, v51
	v_rcp_f32_e32 v52, v52
	v_rcp_f32_e32 v53, v53
	v_pk_mul_f32 v[54:55], v[54:55], v[252:253] op_sel_hi:[1,0]
	v_pk_mul_f32 v[56:57], v[56:57], v[252:253] op_sel_hi:[1,0]
	v_pk_mul_f32 v[50:51], v[50:51], v[252:253] op_sel_hi:[1,0]
	v_pk_mul_f32 v[52:53], v[52:53], v[252:253] op_sel_hi:[1,0]
	v_pk_mul_f32 v[54:55], v[62:63], v[54:55]
	v_pk_mul_f32 v[56:57], v[64:65], v[56:57]
	v_pk_mul_f32 v[50:51], v[58:59], v[50:51]
	v_pk_mul_f32 v[52:53], v[60:61], v[52:53]
	v_cvt_pk_bf16_f32 v58, v54, v55
	v_cvt_pk_bf16_f32 v59, v56, v57
	v_cvt_pk_bf16_f32 v60, v50, v51
	v_cvt_pk_bf16_f32 v61, v52, v53
	global_store_dwordx4 v[146:147], v[58:61], off
	v_add_u32_e32 v253, 144, v142
	v_mad_i64_i32 v[146:147], s[2:3], v253, s57, v[144:145]
	s_waitcnt vmcnt(4)
	v_fmamk_f32 v251, v246, 0x39800000, v162
	v_rsq_f32_e32 v251, v251
	v_pk_mul_f32 v[46:47], v[38:39], v[46:47]
	v_pk_mul_f32 v[48:49], v[40:41], v[48:49]
	v_pk_mul_f32 v[42:43], v[34:35], v[42:43]
	v_pk_mul_f32 v[44:45], v[36:37], v[44:45]
	v_mul_f32_e32 v250, 0xbfb8aa3b, v251
	v_mul_f32_e32 v252, v251, v251
	v_pk_mul_f32 v[38:39], v[38:39], v[250:251] op_sel_hi:[1,0]
	v_pk_mul_f32 v[40:41], v[40:41], v[250:251] op_sel_hi:[1,0]
	v_pk_mul_f32 v[34:35], v[34:35], v[250:251] op_sel_hi:[1,0]
	v_pk_mul_f32 v[36:37], v[36:37], v[250:251] op_sel_hi:[1,0]
	v_exp_f32_e32 v38, v38
	v_exp_f32_e32 v39, v39
	v_exp_f32_e32 v40, v40
	v_exp_f32_e32 v41, v41
	v_exp_f32_e32 v34, v34
	v_exp_f32_e32 v35, v35
	v_exp_f32_e32 v36, v36
	v_exp_f32_e32 v37, v37
	v_pk_add_f32 v[38:39], v[38:39], v[254:255] op_sel_hi:[1,0]
	v_pk_add_f32 v[40:41], v[40:41], v[254:255] op_sel_hi:[1,0]
	v_pk_add_f32 v[34:35], v[34:35], v[254:255] op_sel_hi:[1,0]
	v_pk_add_f32 v[36:37], v[36:37], v[254:255] op_sel_hi:[1,0]
	v_rcp_f32_e32 v38, v38
	v_rcp_f32_e32 v39, v39
	v_rcp_f32_e32 v40, v40
	v_rcp_f32_e32 v41, v41
	v_rcp_f32_e32 v34, v34
	v_rcp_f32_e32 v35, v35
	v_rcp_f32_e32 v36, v36
	v_rcp_f32_e32 v37, v37
	v_pk_mul_f32 v[38:39], v[38:39], v[252:253] op_sel_hi:[1,0]
	v_pk_mul_f32 v[40:41], v[40:41], v[252:253] op_sel_hi:[1,0]
	v_pk_mul_f32 v[34:35], v[34:35], v[252:253] op_sel_hi:[1,0]
	v_pk_mul_f32 v[36:37], v[36:37], v[252:253] op_sel_hi:[1,0]
	v_pk_mul_f32 v[38:39], v[46:47], v[38:39]
	v_pk_mul_f32 v[40:41], v[48:49], v[40:41]
	v_pk_mul_f32 v[34:35], v[42:43], v[34:35]
	v_pk_mul_f32 v[36:37], v[44:45], v[36:37]
	v_cvt_pk_bf16_f32 v42, v38, v39
	v_cvt_pk_bf16_f32 v43, v40, v41
	v_cvt_pk_bf16_f32 v44, v34, v35
	v_cvt_pk_bf16_f32 v45, v36, v37
	global_store_dwordx4 v[146:147], v[42:45], off
	v_add_u32_e32 v253, 160, v142
	v_mad_i64_i32 v[146:147], s[2:3], v253, s57, v[144:145]
	s_waitcnt vmcnt(3)
	v_fmamk_f32 v251, v247, 0x39800000, v162
	v_rsq_f32_e32 v251, v251
	v_pk_mul_f32 v[30:31], v[22:23], v[30:31]
	v_pk_mul_f32 v[32:33], v[24:25], v[32:33]
	v_pk_mul_f32 v[26:27], v[18:19], v[26:27]
	v_pk_mul_f32 v[28:29], v[20:21], v[28:29]
	v_mul_f32_e32 v250, 0xbfb8aa3b, v251
	v_mul_f32_e32 v252, v251, v251
	v_pk_mul_f32 v[22:23], v[22:23], v[250:251] op_sel_hi:[1,0]
	v_pk_mul_f32 v[24:25], v[24:25], v[250:251] op_sel_hi:[1,0]
	v_pk_mul_f32 v[18:19], v[18:19], v[250:251] op_sel_hi:[1,0]
	v_pk_mul_f32 v[20:21], v[20:21], v[250:251] op_sel_hi:[1,0]
	v_exp_f32_e32 v22, v22
	v_exp_f32_e32 v23, v23
	v_exp_f32_e32 v24, v24
	v_exp_f32_e32 v25, v25
	v_exp_f32_e32 v18, v18
	v_exp_f32_e32 v19, v19
	v_exp_f32_e32 v20, v20
	v_exp_f32_e32 v21, v21
	v_pk_add_f32 v[22:23], v[22:23], v[254:255] op_sel_hi:[1,0]
	v_pk_add_f32 v[24:25], v[24:25], v[254:255] op_sel_hi:[1,0]
	v_pk_add_f32 v[18:19], v[18:19], v[254:255] op_sel_hi:[1,0]
	v_pk_add_f32 v[20:21], v[20:21], v[254:255] op_sel_hi:[1,0]
	v_rcp_f32_e32 v22, v22
	v_rcp_f32_e32 v23, v23
	v_rcp_f32_e32 v24, v24
	v_rcp_f32_e32 v25, v25
	v_rcp_f32_e32 v18, v18
	v_rcp_f32_e32 v19, v19
	v_rcp_f32_e32 v20, v20
	v_rcp_f32_e32 v21, v21
	v_pk_mul_f32 v[22:23], v[22:23], v[252:253] op_sel_hi:[1,0]
	v_pk_mul_f32 v[24:25], v[24:25], v[252:253] op_sel_hi:[1,0]
	v_pk_mul_f32 v[18:19], v[18:19], v[252:253] op_sel_hi:[1,0]
	v_pk_mul_f32 v[20:21], v[20:21], v[252:253] op_sel_hi:[1,0]
	v_pk_mul_f32 v[22:23], v[30:31], v[22:23]
	v_pk_mul_f32 v[24:25], v[32:33], v[24:25]
	v_pk_mul_f32 v[18:19], v[26:27], v[18:19]
	v_pk_mul_f32 v[20:21], v[28:29], v[20:21]
	v_cvt_pk_bf16_f32 v26, v22, v23
	v_cvt_pk_bf16_f32 v27, v24, v25
	v_cvt_pk_bf16_f32 v28, v18, v19
	v_cvt_pk_bf16_f32 v29, v20, v21
	global_store_dwordx4 v[146:147], v[26:29], off
	v_add_u32_e32 v253, 176, v142
	v_mad_i64_i32 v[146:147], s[2:3], v253, s57, v[144:145]
	s_mov_b64 s[2:3], -1
	s_waitcnt vmcnt(2)
	v_fmamk_f32 v251, v248, 0x39800000, v162
	v_rsq_f32_e32 v251, v251
	v_pk_mul_f32 v[14:15], v[6:7], v[14:15]
	v_pk_mul_f32 v[16:17], v[8:9], v[16:17]
	v_pk_mul_f32 v[10:11], v[2:3], v[10:11]
	v_pk_mul_f32 v[12:13], v[4:5], v[12:13]
	v_mul_f32_e32 v250, 0xbfb8aa3b, v251
	v_mul_f32_e32 v252, v251, v251
	v_pk_mul_f32 v[6:7], v[6:7], v[250:251] op_sel_hi:[1,0]
	v_pk_mul_f32 v[8:9], v[8:9], v[250:251] op_sel_hi:[1,0]
	v_pk_mul_f32 v[2:3], v[2:3], v[250:251] op_sel_hi:[1,0]
	v_pk_mul_f32 v[4:5], v[4:5], v[250:251] op_sel_hi:[1,0]
	v_exp_f32_e32 v6, v6
	v_exp_f32_e32 v7, v7
	v_exp_f32_e32 v8, v8
	v_exp_f32_e32 v9, v9
	v_exp_f32_e32 v2, v2
	v_exp_f32_e32 v3, v3
	v_exp_f32_e32 v4, v4
	v_exp_f32_e32 v5, v5
	v_pk_add_f32 v[6:7], v[6:7], v[254:255] op_sel_hi:[1,0]
	v_pk_add_f32 v[8:9], v[8:9], v[254:255] op_sel_hi:[1,0]
	v_pk_add_f32 v[2:3], v[2:3], v[254:255] op_sel_hi:[1,0]
	v_pk_add_f32 v[4:5], v[4:5], v[254:255] op_sel_hi:[1,0]
	v_rcp_f32_e32 v6, v6
	v_rcp_f32_e32 v7, v7
	v_rcp_f32_e32 v8, v8
	v_rcp_f32_e32 v9, v9
	v_rcp_f32_e32 v2, v2
	v_rcp_f32_e32 v3, v3
	v_rcp_f32_e32 v4, v4
	v_rcp_f32_e32 v5, v5
	v_pk_mul_f32 v[6:7], v[6:7], v[252:253] op_sel_hi:[1,0]
	v_pk_mul_f32 v[8:9], v[8:9], v[252:253] op_sel_hi:[1,0]
	v_pk_mul_f32 v[2:3], v[2:3], v[252:253] op_sel_hi:[1,0]
	v_pk_mul_f32 v[4:5], v[4:5], v[252:253] op_sel_hi:[1,0]
	v_pk_mul_f32 v[6:7], v[14:15], v[6:7]
	v_pk_mul_f32 v[8:9], v[16:17], v[8:9]
	v_pk_mul_f32 v[2:3], v[10:11], v[2:3]
	v_pk_mul_f32 v[4:5], v[12:13], v[4:5]
	v_cvt_pk_bf16_f32 v10, v6, v7
	v_cvt_pk_bf16_f32 v11, v8, v9
	v_cvt_pk_bf16_f32 v12, v2, v3
	v_cvt_pk_bf16_f32 v13, v4, v5
	global_store_dwordx4 v[146:147], v[10:13], off
	s_cbranch_vccnz .LBB0_1258
	s_andn2_b64 vcc, exec, s[0:1]
	s_cbranch_vccnz .LBB0_1257
	s_barrier
	s_branch .LBB0_1257

.LBB0_1542:
	v_lshl_add_u32 v142, s18, 8, v153
	v_ashrrev_i32_e32 v143, 31, v142
	v_lshl_add_u64 v[146:147], v[142:143], 2, s[4:5]
	global_load_dword v241, v[146:147], off
	global_load_dword v242, v[146:147], off offset:64
	global_load_dword v243, v[146:147], off offset:128
	global_load_dword v244, v[146:147], off offset:192
	global_load_dword v245, v[146:147], off offset:512
	global_load_dword v246, v[146:147], off offset:576
	global_load_dword v247, v[146:147], off offset:640
	global_load_dword v248, v[146:147], off offset:704
	v_and_b32_e32 v143, 0xff, v0
	v_bfe_u32 v145, v0, 8, 1
	v_lshl_add_u32 v144, s18, 8, v143
	v_add_u32_e32 v144, 0x800, v144
	v_lshlrev_b32_e32 v144, 13, v144
	v_lshl_or_b32 v144, v145, 7, v144
	s_add_u32 s98, s84, 0x2f000000
	s_addc_u32 s99, s85, 0
	global_load_dword v249, v144, s[98:99]
	v_lshl_add_u32 v143, s16, 8, v143
	v_lshlrev_b32_e32 v143, 13, v143
	v_lshl_or_b32 v143, v145, 7, v143
	s_add_u32 s98, s84, 0xfc00000
	s_addc_u32 s99, s85, 0
	global_load_dword v249, v143, s[98:99]
	v_lshl_or_b32 v144, s16, 7, v158
	v_ashrrev_i32_e32 v145, 31, v144
	v_mov_b32_e32 v254, 1.0
	v_lshl_add_u64 v[144:145], v[144:145], 1, s[6:7]
	s_andn2_b64 vcc, exec, s[20:21]
	v_mad_i64_i32 v[146:147], s[2:3], v142, s50, v[144:145]
	s_waitcnt vmcnt(9)
	v_fmamk_f32 v251, v241, 0x39800000, v161
	v_rsq_f32_e32 v251, v251
	v_pk_mul_f32 v[126:127], v[118:119], v[126:127]
	v_pk_mul_f32 v[128:129], v[120:121], v[128:129]
	v_pk_mul_f32 v[122:123], v[114:115], v[122:123]
	v_pk_mul_f32 v[124:125], v[116:117], v[124:125]
	v_mul_f32_e32 v250, 0xbfb8aa3b, v251
	v_mul_f32_e32 v252, v251, v251
	v_pk_mul_f32 v[118:119], v[118:119], v[250:251] op_sel_hi:[1,0]
	v_pk_mul_f32 v[120:121], v[120:121], v[250:251] op_sel_hi:[1,0]
	v_pk_mul_f32 v[114:115], v[114:115], v[250:251] op_sel_hi:[1,0]
	v_pk_mul_f32 v[116:117], v[116:117], v[250:251] op_sel_hi:[1,0]
	v_exp_f32_e32 v118, v118
	v_exp_f32_e32 v119, v119
	v_exp_f32_e32 v120, v120
	v_exp_f32_e32 v121, v121
	v_exp_f32_e32 v114, v114
	v_exp_f32_e32 v115, v115
	v_exp_f32_e32 v116, v116
	v_exp_f32_e32 v117, v117
	v_pk_add_f32 v[118:119], v[118:119], v[254:255] op_sel_hi:[1,0]
	v_pk_add_f32 v[120:121], v[120:121], v[254:255] op_sel_hi:[1,0]
	v_pk_add_f32 v[114:115], v[114:115], v[254:255] op_sel_hi:[1,0]
	v_pk_add_f32 v[116:117], v[116:117], v[254:255] op_sel_hi:[1,0]
	v_rcp_f32_e32 v118, v118
	v_rcp_f32_e32 v119, v119
	v_rcp_f32_e32 v120, v120
	v_rcp_f32_e32 v121, v121
	v_rcp_f32_e32 v114, v114
	v_rcp_f32_e32 v115, v115
	v_rcp_f32_e32 v116, v116
	v_rcp_f32_e32 v117, v117
	v_pk_mul_f32 v[118:119], v[118:119], v[252:253] op_sel_hi:[1,0]
	v_pk_mul_f32 v[120:121], v[120:121], v[252:253] op_sel_hi:[1,0]
	v_pk_mul_f32 v[114:115], v[114:115], v[252:253] op_sel_hi:[1,0]
	v_pk_mul_f32 v[116:117], v[116:117], v[252:253] op_sel_hi:[1,0]
	v_pk_mul_f32 v[118:119], v[126:127], v[118:119]
	v_pk_mul_f32 v[120:121], v[128:129], v[120:121]
	v_pk_mul_f32 v[114:115], v[122:123], v[114:115]
	v_pk_mul_f32 v[116:117], v[124:125], v[116:117]
	v_cvt_pk_bf16_f32 v122, v118, v119
	v_cvt_pk_bf16_f32 v123, v120, v121
	v_cvt_pk_bf16_f32 v124, v114, v115
	v_cvt_pk_bf16_f32 v125, v116, v117
	global_store_dwordx4 v[146:147], v[122:125], off
	v_add_u32_e32 v253, 16, v142
	v_mad_i64_i32 v[146:147], s[2:3], v253, s50, v[144:145]
	s_waitcnt vmcnt(8)
	v_fmamk_f32 v251, v242, 0x39800000, v161
	v_rsq_f32_e32 v251, v251
	v_pk_mul_f32 v[110:111], v[102:103], v[110:111]
	v_pk_mul_f32 v[112:113], v[104:105], v[112:113]
	v_pk_mul_f32 v[106:107], v[98:99], v[106:107]
	v_pk_mul_f32 v[108:109], v[100:101], v[108:109]
	v_mul_f32_e32 v250, 0xbfb8aa3b, v251
	v_mul_f32_e32 v252, v251, v251
	v_pk_mul_f32 v[102:103], v[102:103], v[250:251] op_sel_hi:[1,0]
	v_pk_mul_f32 v[104:105], v[104:105], v[250:251] op_sel_hi:[1,0]
	v_pk_mul_f32 v[98:99], v[98:99], v[250:251] op_sel_hi:[1,0]
	v_pk_mul_f32 v[100:101], v[100:101], v[250:251] op_sel_hi:[1,0]
	v_exp_f32_e32 v102, v102
	v_exp_f32_e32 v103, v103
	v_exp_f32_e32 v104, v104
	v_exp_f32_e32 v105, v105
	v_exp_f32_e32 v98, v98
	v_exp_f32_e32 v99, v99
	v_exp_f32_e32 v100, v100
	v_exp_f32_e32 v101, v101
	v_pk_add_f32 v[102:103], v[102:103], v[254:255] op_sel_hi:[1,0]
	v_pk_add_f32 v[104:105], v[104:105], v[254:255] op_sel_hi:[1,0]
	v_pk_add_f32 v[98:99], v[98:99], v[254:255] op_sel_hi:[1,0]
	v_pk_add_f32 v[100:101], v[100:101], v[254:255] op_sel_hi:[1,0]
	v_rcp_f32_e32 v102, v102
	v_rcp_f32_e32 v103, v103
	v_rcp_f32_e32 v104, v104
	v_rcp_f32_e32 v105, v105
	v_rcp_f32_e32 v98, v98
	v_rcp_f32_e32 v99, v99
	v_rcp_f32_e32 v100, v100
	v_rcp_f32_e32 v101, v101
	v_pk_mul_f32 v[102:103], v[102:103], v[252:253] op_sel_hi:[1,0]
	v_pk_mul_f32 v[104:105], v[104:105], v[252:253] op_sel_hi:[1,0]
	v_pk_mul_f32 v[98:99], v[98:99], v[252:253] op_sel_hi:[1,0]
	v_pk_mul_f32 v[100:101], v[100:101], v[252:253] op_sel_hi:[1,0]
	v_pk_mul_f32 v[102:103], v[110:111], v[102:103]
	v_pk_mul_f32 v[104:105], v[112:113], v[104:105]
	v_pk_mul_f32 v[98:99], v[106:107], v[98:99]
	v_pk_mul_f32 v[100:101], v[108:109], v[100:101]
	v_cvt_pk_bf16_f32 v106, v102, v103
	v_cvt_pk_bf16_f32 v107, v104, v105
	v_cvt_pk_bf16_f32 v108, v98, v99
	v_cvt_pk_bf16_f32 v109, v100, v101
	global_store_dwordx4 v[146:147], v[106:109], off
	v_add_u32_e32 v253, 32, v142
	v_mad_i64_i32 v[146:147], s[2:3], v253, s50, v[144:145]
	s_waitcnt vmcnt(7)
	v_fmamk_f32 v251, v243, 0x39800000, v161
	v_rsq_f32_e32 v251, v251
	v_pk_mul_f32 v[94:95], v[86:87], v[94:95]
	v_pk_mul_f32 v[96:97], v[88:89], v[96:97]
	v_pk_mul_f32 v[90:91], v[82:83], v[90:91]
	v_pk_mul_f32 v[92:93], v[84:85], v[92:93]
	v_mul_f32_e32 v250, 0xbfb8aa3b, v251
	v_mul_f32_e32 v252, v251, v251
	v_pk_mul_f32 v[86:87], v[86:87], v[250:251] op_sel_hi:[1,0]
	v_pk_mul_f32 v[88:89], v[88:89], v[250:251] op_sel_hi:[1,0]
	v_pk_mul_f32 v[82:83], v[82:83], v[250:251] op_sel_hi:[1,0]
	v_pk_mul_f32 v[84:85], v[84:85], v[250:251] op_sel_hi:[1,0]
	v_exp_f32_e32 v86, v86
	v_exp_f32_e32 v87, v87
	v_exp_f32_e32 v88, v88
	v_exp_f32_e32 v89, v89
	v_exp_f32_e32 v82, v82
	v_exp_f32_e32 v83, v83
	v_exp_f32_e32 v84, v84
	v_exp_f32_e32 v85, v85
	v_pk_add_f32 v[86:87], v[86:87], v[254:255] op_sel_hi:[1,0]
	v_pk_add_f32 v[88:89], v[88:89], v[254:255] op_sel_hi:[1,0]
	v_pk_add_f32 v[82:83], v[82:83], v[254:255] op_sel_hi:[1,0]
	v_pk_add_f32 v[84:85], v[84:85], v[254:255] op_sel_hi:[1,0]
	v_rcp_f32_e32 v86, v86
	v_rcp_f32_e32 v87, v87
	v_rcp_f32_e32 v88, v88
	v_rcp_f32_e32 v89, v89
	v_rcp_f32_e32 v82, v82
	v_rcp_f32_e32 v83, v83
	v_rcp_f32_e32 v84, v84
	v_rcp_f32_e32 v85, v85
	v_pk_mul_f32 v[86:87], v[86:87], v[252:253] op_sel_hi:[1,0]
	v_pk_mul_f32 v[88:89], v[88:89], v[252:253] op_sel_hi:[1,0]
	v_pk_mul_f32 v[82:83], v[82:83], v[252:253] op_sel_hi:[1,0]
	v_pk_mul_f32 v[84:85], v[84:85], v[252:253] op_sel_hi:[1,0]
	v_pk_mul_f32 v[86:87], v[94:95], v[86:87]
	v_pk_mul_f32 v[88:89], v[96:97], v[88:89]
	v_pk_mul_f32 v[82:83], v[90:91], v[82:83]
	v_pk_mul_f32 v[84:85], v[92:93], v[84:85]
	v_cvt_pk_bf16_f32 v90, v86, v87
	v_cvt_pk_bf16_f32 v91, v88, v89
	v_cvt_pk_bf16_f32 v92, v82, v83
	v_cvt_pk_bf16_f32 v93, v84, v85
	global_store_dwordx4 v[146:147], v[90:93], off
	v_add_u32_e32 v253, 48, v142
	v_mad_i64_i32 v[146:147], s[2:3], v253, s50, v[144:145]
	s_waitcnt vmcnt(6)
	v_fmamk_f32 v251, v244, 0x39800000, v161
	v_rsq_f32_e32 v251, v251
	v_pk_mul_f32 v[78:79], v[70:71], v[78:79]
	v_pk_mul_f32 v[80:81], v[72:73], v[80:81]
	v_pk_mul_f32 v[74:75], v[66:67], v[74:75]
	v_pk_mul_f32 v[76:77], v[68:69], v[76:77]
	v_mul_f32_e32 v250, 0xbfb8aa3b, v251
	v_mul_f32_e32 v252, v251, v251
	v_pk_mul_f32 v[70:71], v[70:71], v[250:251] op_sel_hi:[1,0]
	v_pk_mul_f32 v[72:73], v[72:73], v[250:251] op_sel_hi:[1,0]
	v_pk_mul_f32 v[66:67], v[66:67], v[250:251] op_sel_hi:[1,0]
	v_pk_mul_f32 v[68:69], v[68:69], v[250:251] op_sel_hi:[1,0]
	v_exp_f32_e32 v70, v70
	v_exp_f32_e32 v71, v71
	v_exp_f32_e32 v72, v72
	v_exp_f32_e32 v73, v73
	v_exp_f32_e32 v66, v66
	v_exp_f32_e32 v67, v67
	v_exp_f32_e32 v68, v68
	v_exp_f32_e32 v69, v69
	v_pk_add_f32 v[70:71], v[70:71], v[254:255] op_sel_hi:[1,0]
	v_pk_add_f32 v[72:73], v[72:73], v[254:255] op_sel_hi:[1,0]
	v_pk_add_f32 v[66:67], v[66:67], v[254:255] op_sel_hi:[1,0]
	v_pk_add_f32 v[68:69], v[68:69], v[254:255] op_sel_hi:[1,0]
	v_rcp_f32_e32 v70, v70
	v_rcp_f32_e32 v71, v71
	v_rcp_f32_e32 v72, v72
	v_rcp_f32_e32 v73, v73
	v_rcp_f32_e32 v66, v66
	v_rcp_f32_e32 v67, v67
	v_rcp_f32_e32 v68, v68
	v_rcp_f32_e32 v69, v69
	v_pk_mul_f32 v[70:71], v[70:71], v[252:253] op_sel_hi:[1,0]
	v_pk_mul_f32 v[72:73], v[72:73], v[252:253] op_sel_hi:[1,0]
	v_pk_mul_f32 v[66:67], v[66:67], v[252:253] op_sel_hi:[1,0]
	v_pk_mul_f32 v[68:69], v[68:69], v[252:253] op_sel_hi:[1,0]
	v_pk_mul_f32 v[70:71], v[78:79], v[70:71]
	v_pk_mul_f32 v[72:73], v[80:81], v[72:73]
	v_pk_mul_f32 v[66:67], v[74:75], v[66:67]
	v_pk_mul_f32 v[68:69], v[76:77], v[68:69]
	v_cvt_pk_bf16_f32 v74, v70, v71
	v_cvt_pk_bf16_f32 v75, v72, v73
	v_cvt_pk_bf16_f32 v76, v66, v67
	v_cvt_pk_bf16_f32 v77, v68, v69
	global_store_dwordx4 v[146:147], v[74:77], off
	v_add_u32_e32 v253, 128, v142
	v_mad_i64_i32 v[146:147], s[2:3], v253, s50, v[144:145]
	s_waitcnt vmcnt(5)
	v_fmamk_f32 v251, v245, 0x39800000, v161
	v_rsq_f32_e32 v251, v251
	v_pk_mul_f32 v[62:63], v[54:55], v[62:63]
	v_pk_mul_f32 v[64:65], v[56:57], v[64:65]
	v_pk_mul_f32 v[58:59], v[50:51], v[58:59]
	v_pk_mul_f32 v[60:61], v[52:53], v[60:61]
	v_mul_f32_e32 v250, 0xbfb8aa3b, v251
	v_mul_f32_e32 v252, v251, v251
	v_pk_mul_f32 v[54:55], v[54:55], v[250:251] op_sel_hi:[1,0]
	v_pk_mul_f32 v[56:57], v[56:57], v[250:251] op_sel_hi:[1,0]
	v_pk_mul_f32 v[50:51], v[50:51], v[250:251] op_sel_hi:[1,0]
	v_pk_mul_f32 v[52:53], v[52:53], v[250:251] op_sel_hi:[1,0]
	v_exp_f32_e32 v54, v54
	v_exp_f32_e32 v55, v55
	v_exp_f32_e32 v56, v56
	v_exp_f32_e32 v57, v57
	v_exp_f32_e32 v50, v50
	v_exp_f32_e32 v51, v51
	v_exp_f32_e32 v52, v52
	v_exp_f32_e32 v53, v53
	v_pk_add_f32 v[54:55], v[54:55], v[254:255] op_sel_hi:[1,0]
	v_pk_add_f32 v[56:57], v[56:57], v[254:255] op_sel_hi:[1,0]
	v_pk_add_f32 v[50:51], v[50:51], v[254:255] op_sel_hi:[1,0]
	v_pk_add_f32 v[52:53], v[52:53], v[254:255] op_sel_hi:[1,0]
	v_rcp_f32_e32 v54, v54
	v_rcp_f32_e32 v55, v55
	v_rcp_f32_e32 v56, v56
	v_rcp_f32_e32 v57, v57
	v_rcp_f32_e32 v50, v50
	v_rcp_f32_e32 v51, v51
	v_rcp_f32_e32 v52, v52
	v_rcp_f32_e32 v53, v53
	v_pk_mul_f32 v[54:55], v[54:55], v[252:253] op_sel_hi:[1,0]
	v_pk_mul_f32 v[56:57], v[56:57], v[252:253] op_sel_hi:[1,0]
	v_pk_mul_f32 v[50:51], v[50:51], v[252:253] op_sel_hi:[1,0]
	v_pk_mul_f32 v[52:53], v[52:53], v[252:253] op_sel_hi:[1,0]
	v_pk_mul_f32 v[54:55], v[62:63], v[54:55]
	v_pk_mul_f32 v[56:57], v[64:65], v[56:57]
	v_pk_mul_f32 v[50:51], v[58:59], v[50:51]
	v_pk_mul_f32 v[52:53], v[60:61], v[52:53]
	v_cvt_pk_bf16_f32 v58, v54, v55
	v_cvt_pk_bf16_f32 v59, v56, v57
	v_cvt_pk_bf16_f32 v60, v50, v51
	v_cvt_pk_bf16_f32 v61, v52, v53
	global_store_dwordx4 v[146:147], v[58:61], off
	v_add_u32_e32 v253, 144, v142
	v_mad_i64_i32 v[146:147], s[2:3], v253, s50, v[144:145]
	s_waitcnt vmcnt(4)
	v_fmamk_f32 v251, v246, 0x39800000, v161
	v_rsq_f32_e32 v251, v251
	v_pk_mul_f32 v[46:47], v[38:39], v[46:47]
	v_pk_mul_f32 v[48:49], v[40:41], v[48:49]
	v_pk_mul_f32 v[42:43], v[34:35], v[42:43]
	v_pk_mul_f32 v[44:45], v[36:37], v[44:45]
	v_mul_f32_e32 v250, 0xbfb8aa3b, v251
	v_mul_f32_e32 v252, v251, v251
	v_pk_mul_f32 v[38:39], v[38:39], v[250:251] op_sel_hi:[1,0]
	v_pk_mul_f32 v[40:41], v[40:41], v[250:251] op_sel_hi:[1,0]
	v_pk_mul_f32 v[34:35], v[34:35], v[250:251] op_sel_hi:[1,0]
	v_pk_mul_f32 v[36:37], v[36:37], v[250:251] op_sel_hi:[1,0]
	v_exp_f32_e32 v38, v38
	v_exp_f32_e32 v39, v39
	v_exp_f32_e32 v40, v40
	v_exp_f32_e32 v41, v41
	v_exp_f32_e32 v34, v34
	v_exp_f32_e32 v35, v35
	v_exp_f32_e32 v36, v36
	v_exp_f32_e32 v37, v37
	v_pk_add_f32 v[38:39], v[38:39], v[254:255] op_sel_hi:[1,0]
	v_pk_add_f32 v[40:41], v[40:41], v[254:255] op_sel_hi:[1,0]
	v_pk_add_f32 v[34:35], v[34:35], v[254:255] op_sel_hi:[1,0]
	v_pk_add_f32 v[36:37], v[36:37], v[254:255] op_sel_hi:[1,0]
	v_rcp_f32_e32 v38, v38
	v_rcp_f32_e32 v39, v39
	v_rcp_f32_e32 v40, v40
	v_rcp_f32_e32 v41, v41
	v_rcp_f32_e32 v34, v34
	v_rcp_f32_e32 v35, v35
	v_rcp_f32_e32 v36, v36
	v_rcp_f32_e32 v37, v37
	v_pk_mul_f32 v[38:39], v[38:39], v[252:253] op_sel_hi:[1,0]
	v_pk_mul_f32 v[40:41], v[40:41], v[252:253] op_sel_hi:[1,0]
	v_pk_mul_f32 v[34:35], v[34:35], v[252:253] op_sel_hi:[1,0]
	v_pk_mul_f32 v[36:37], v[36:37], v[252:253] op_sel_hi:[1,0]
	v_pk_mul_f32 v[38:39], v[46:47], v[38:39]
	v_pk_mul_f32 v[40:41], v[48:49], v[40:41]
	v_pk_mul_f32 v[34:35], v[42:43], v[34:35]
	v_pk_mul_f32 v[36:37], v[44:45], v[36:37]
	v_cvt_pk_bf16_f32 v42, v38, v39
	v_cvt_pk_bf16_f32 v43, v40, v41
	v_cvt_pk_bf16_f32 v44, v34, v35
	v_cvt_pk_bf16_f32 v45, v36, v37
	global_store_dwordx4 v[146:147], v[42:45], off
	v_add_u32_e32 v253, 160, v142
	v_mad_i64_i32 v[146:147], s[2:3], v253, s50, v[144:145]
	s_waitcnt vmcnt(3)
	v_fmamk_f32 v251, v247, 0x39800000, v161
	v_rsq_f32_e32 v251, v251
	v_pk_mul_f32 v[30:31], v[22:23], v[30:31]
	v_pk_mul_f32 v[32:33], v[24:25], v[32:33]
	v_pk_mul_f32 v[26:27], v[18:19], v[26:27]
	v_pk_mul_f32 v[28:29], v[20:21], v[28:29]
	v_mul_f32_e32 v250, 0xbfb8aa3b, v251
	v_mul_f32_e32 v252, v251, v251
	v_pk_mul_f32 v[22:23], v[22:23], v[250:251] op_sel_hi:[1,0]
	v_pk_mul_f32 v[24:25], v[24:25], v[250:251] op_sel_hi:[1,0]
	v_pk_mul_f32 v[18:19], v[18:19], v[250:251] op_sel_hi:[1,0]
	v_pk_mul_f32 v[20:21], v[20:21], v[250:251] op_sel_hi:[1,0]
	v_exp_f32_e32 v22, v22
	v_exp_f32_e32 v23, v23
	v_exp_f32_e32 v24, v24
	v_exp_f32_e32 v25, v25
	v_exp_f32_e32 v18, v18
	v_exp_f32_e32 v19, v19
	v_exp_f32_e32 v20, v20
	v_exp_f32_e32 v21, v21
	v_pk_add_f32 v[22:23], v[22:23], v[254:255] op_sel_hi:[1,0]
	v_pk_add_f32 v[24:25], v[24:25], v[254:255] op_sel_hi:[1,0]
	v_pk_add_f32 v[18:19], v[18:19], v[254:255] op_sel_hi:[1,0]
	v_pk_add_f32 v[20:21], v[20:21], v[254:255] op_sel_hi:[1,0]
	v_rcp_f32_e32 v22, v22
	v_rcp_f32_e32 v23, v23
	v_rcp_f32_e32 v24, v24
	v_rcp_f32_e32 v25, v25
	v_rcp_f32_e32 v18, v18
	v_rcp_f32_e32 v19, v19
	v_rcp_f32_e32 v20, v20
	v_rcp_f32_e32 v21, v21
	v_pk_mul_f32 v[22:23], v[22:23], v[252:253] op_sel_hi:[1,0]
	v_pk_mul_f32 v[24:25], v[24:25], v[252:253] op_sel_hi:[1,0]
	v_pk_mul_f32 v[18:19], v[18:19], v[252:253] op_sel_hi:[1,0]
	v_pk_mul_f32 v[20:21], v[20:21], v[252:253] op_sel_hi:[1,0]
	v_pk_mul_f32 v[22:23], v[30:31], v[22:23]
	v_pk_mul_f32 v[24:25], v[32:33], v[24:25]
	v_pk_mul_f32 v[18:19], v[26:27], v[18:19]
	v_pk_mul_f32 v[20:21], v[28:29], v[20:21]
	v_cvt_pk_bf16_f32 v26, v22, v23
	v_cvt_pk_bf16_f32 v27, v24, v25
	v_cvt_pk_bf16_f32 v28, v18, v19
	v_cvt_pk_bf16_f32 v29, v20, v21
	global_store_dwordx4 v[146:147], v[26:29], off
	v_add_u32_e32 v253, 176, v142
	v_mad_i64_i32 v[146:147], s[2:3], v253, s50, v[144:145]
	s_mov_b64 s[2:3], -1
	s_waitcnt vmcnt(2)
	v_fmamk_f32 v251, v248, 0x39800000, v161
	v_rsq_f32_e32 v251, v251
	v_pk_mul_f32 v[14:15], v[6:7], v[14:15]
	v_pk_mul_f32 v[16:17], v[8:9], v[16:17]
	v_pk_mul_f32 v[10:11], v[2:3], v[10:11]
	v_pk_mul_f32 v[12:13], v[4:5], v[12:13]
	v_mul_f32_e32 v250, 0xbfb8aa3b, v251
	v_mul_f32_e32 v252, v251, v251
	v_pk_mul_f32 v[6:7], v[6:7], v[250:251] op_sel_hi:[1,0]
	v_pk_mul_f32 v[8:9], v[8:9], v[250:251] op_sel_hi:[1,0]
	v_pk_mul_f32 v[2:3], v[2:3], v[250:251] op_sel_hi:[1,0]
	v_pk_mul_f32 v[4:5], v[4:5], v[250:251] op_sel_hi:[1,0]
	v_exp_f32_e32 v6, v6
	v_exp_f32_e32 v7, v7
	v_exp_f32_e32 v8, v8
	v_exp_f32_e32 v9, v9
	v_exp_f32_e32 v2, v2
	v_exp_f32_e32 v3, v3
	v_exp_f32_e32 v4, v4
	v_exp_f32_e32 v5, v5
	v_pk_add_f32 v[6:7], v[6:7], v[254:255] op_sel_hi:[1,0]
	v_pk_add_f32 v[8:9], v[8:9], v[254:255] op_sel_hi:[1,0]
	v_pk_add_f32 v[2:3], v[2:3], v[254:255] op_sel_hi:[1,0]
	v_pk_add_f32 v[4:5], v[4:5], v[254:255] op_sel_hi:[1,0]
	v_rcp_f32_e32 v6, v6
	v_rcp_f32_e32 v7, v7
	v_rcp_f32_e32 v8, v8
	v_rcp_f32_e32 v9, v9
	v_rcp_f32_e32 v2, v2
	v_rcp_f32_e32 v3, v3
	v_rcp_f32_e32 v4, v4
	v_rcp_f32_e32 v5, v5
	v_pk_mul_f32 v[6:7], v[6:7], v[252:253] op_sel_hi:[1,0]
	v_pk_mul_f32 v[8:9], v[8:9], v[252:253] op_sel_hi:[1,0]
	v_pk_mul_f32 v[2:3], v[2:3], v[252:253] op_sel_hi:[1,0]
	v_pk_mul_f32 v[4:5], v[4:5], v[252:253] op_sel_hi:[1,0]
	v_pk_mul_f32 v[6:7], v[14:15], v[6:7]
	v_pk_mul_f32 v[8:9], v[16:17], v[8:9]
	v_pk_mul_f32 v[2:3], v[10:11], v[2:3]
	v_pk_mul_f32 v[4:5], v[12:13], v[4:5]
	v_cvt_pk_bf16_f32 v10, v6, v7
	v_cvt_pk_bf16_f32 v11, v8, v9
	v_cvt_pk_bf16_f32 v12, v2, v3
	v_cvt_pk_bf16_f32 v13, v4, v5
	global_store_dwordx4 v[146:147], v[10:13], off
	s_cbranch_vccnz .LBB0_1464
	s_andn2_b64 vcc, exec, s[0:1]
	s_cbranch_vccnz .LBB0_1463
	s_barrier
	s_branch .LBB0_1463
